# adaLN passes 1 and 2 (P4, P10): all 16 per-token loads issued up front instead of 5 dependent round trips
# speedup vs baseline: 1.0383x; 1.0383x over previous
.LBB0_604:
	s_or_b64 exec, exec, s[46:47]
	v_lshl_add_u64 v[2:3], v[2:3], 0, v[0:1]
	global_load_dwordx4 v[36:39], v[2:3], off
	global_load_dwordx4 v[40:43], v[2:3], off offset:1024
	global_load_dwordx4 v[44:47], v[2:3], off offset:2048
	s_nop 0
	global_load_dwordx4 v[2:5], v[2:3], off offset:3072
	s_nop 0
	global_load_dwordx4 v[48:51], v[8:9], off
	global_load_dwordx4 v[78:81], v[10:11], off
	global_load_dwordx4 v[90:93], v[12:13], off
	global_load_dwordx4 v[102:105], v[14:15], off
	v_min_i32_e32 v19, 0x4000, v6
	v_ashrrev_i32_e32 v19, 11, v19
	v_mul_hi_i32_i24_e32 v25, 0x9000, v19
	v_mul_i32_i24_e32 v24, 0x9000, v19
	v_lshl_add_u64 v[24:25], s[16:17], 0, v[24:25]
	v_lshl_add_u64 v[26:27], v[24:25], 0, s[38:39]
	v_lshl_add_u64 v[28:29], v[26:27], 0, v[0:1]
	global_load_dwordx4 v[52:55], v[28:29], off
	global_load_dwordx4 v[82:85], v[28:29], off offset:1024
	global_load_dwordx4 v[94:97], v[28:29], off offset:2048
	global_load_dwordx4 v[106:109], v[28:29], off offset:3072
	v_lshl_add_u64 v[28:29], v[24:25], 0, v[0:1]
	global_load_dwordx4 v[56:59], v[28:29], off
	global_load_dwordx4 v[86:89], v[28:29], off offset:1024
	global_load_dwordx4 v[98:101], v[28:29], off offset:2048
	global_load_dwordx4 v[110:113], v[28:29], off offset:3072
	s_mov_b32 s4, s42
	s_waitcnt vmcnt(15)
	v_mov_b32_e32 v60, v37
	s_waitcnt vmcnt(14)
	v_mov_b32_e32 v61, v41
	v_mov_b32_e32 v24, v36
	v_mov_b32_e32 v25, v40
	s_waitcnt vmcnt(13)
	v_mov_b32_e32 v68, v45
	s_waitcnt vmcnt(12)
	v_mov_b32_e32 v69, v3
	v_pk_mul_f32 v[60:61], v[60:61], v[60:61]
	v_mov_b32_e32 v62, v38
	v_mov_b32_e32 v63, v42
	v_mov_b32_e32 v66, v44
	v_mov_b32_e32 v67, v2
	v_pk_mul_f32 v[68:69], v[68:69], v[68:69]
	v_pk_fma_f32 v[24:25], v[24:25], v[24:25], v[60:61]
	v_mov_b32_e32 v64, v39
	v_mov_b32_e32 v65, v43
	v_mov_b32_e32 v70, v46
	v_mov_b32_e32 v71, v4
	v_pk_fma_f32 v[60:61], v[66:67], v[66:67], v[68:69]
	v_pk_fma_f32 v[24:25], v[62:63], v[62:63], v[24:25]
	v_mov_b32_e32 v72, v47
	v_mov_b32_e32 v73, v5
	v_pk_fma_f32 v[60:61], v[70:71], v[70:71], v[60:61]
	v_pk_fma_f32 v[24:25], v[64:65], v[64:65], v[24:25]
	v_pk_fma_f32 v[60:61], v[72:73], v[72:73], v[60:61]
	v_add_f32_e32 v19, v24, v25
	v_add_f32_e32 v19, v19, v60
	v_add_f32_e32 v19, v19, v61
	ds_bpermute_b32 v21, v30, v19
	v_lshlrev_b64 v[24:25], 11, v[6:7]
	s_waitcnt vmcnt(11)
	v_mov_b32_e32 v60, v48
	v_mov_b32_e32 v48, v36
	v_mov_b32_e32 v36, v37
	s_waitcnt lgkmcnt(0)
	v_add_f32_e32 v19, v19, v21
	ds_bpermute_b32 v21, v31, v19
	v_mov_b32_e32 v37, v39
	s_waitcnt vmcnt(3)
	v_mov_b32_e32 v62, v56
	v_mov_b32_e32 v61, v50
	v_mov_b32_e32 v50, v49
	s_waitcnt lgkmcnt(0)
	v_add_f32_e32 v21, v19, v21
	ds_bpermute_b32 v23, v32, v21
	v_mov_b32_e32 v49, v38
	v_mov_b32_e32 v39, v54
	v_mov_b32_e32 v54, v53
	v_mov_b32_e32 v38, v52
	s_waitcnt lgkmcnt(0)
	v_add_f32_e32 v7, v21, v23
	ds_bpermute_b32 v21, v33, v7
	v_mov_b32_e32 v63, v58
	v_mov_b32_e32 v58, v57
	v_pk_add_f32 v[52:53], v[54:55], 1.0 op_sel_hi:[1,0]
	v_pk_add_f32 v[38:39], v[38:39], 1.0 op_sel_hi:[1,0]
	s_waitcnt lgkmcnt(0)
	v_add_f32_e32 v7, v7, v21
	ds_bpermute_b32 v21, v34, v7
	v_lshl_add_u64 v[24:25], v[16:17], 0, v[24:25]
	v_mov_b32_e32 v19, v1
	s_waitcnt lgkmcnt(0)
	v_add_f32_e32 v7, v7, v21
	ds_bpermute_b32 v21, v35, v7
	s_waitcnt lgkmcnt(0)
	v_add_f32_e32 v7, v7, v21
	v_fmamk_f32 v7, v7, 0x3a800000, v174
	v_mul_f32_e32 v21, 0x4b800000, v7
	v_cmp_gt_f32_e32 vcc, s27, v7
	s_nop 1
	v_cndmask_b32_e32 v7, v7, v21, vcc
	v_rsq_f32_e32 v7, v7
	s_nop 0
	v_mul_f32_e32 v21, 0x45800000, v7
	v_cndmask_b32_e32 v56, v7, v21, vcc
	v_pk_mul_f32 v[36:37], v[36:37], v[56:57] op_sel_hi:[1,0]
	v_pk_mul_f32 v[48:49], v[48:49], v[56:57] op_sel_hi:[1,0]
	v_pk_mul_f32 v[36:37], v[50:51], v[36:37]
	v_pk_mul_f32 v[48:49], v[60:61], v[48:49]
	v_pk_fma_f32 v[36:37], v[52:53], v[36:37], v[58:59]
	v_pk_fma_f32 v[38:39], v[38:39], v[48:49], v[62:63]
	v_and_b32_sdwa v23, v37, v177 dst_sel:DWORD dst_unused:UNUSED_PAD src0_sel:WORD_1 src1_sel:DWORD
	v_and_b32_sdwa v48, v36, v177 dst_sel:DWORD dst_unused:UNUSED_PAD src0_sel:WORD_1 src1_sel:DWORD
	v_and_b32_sdwa v7, v39, v177 dst_sel:DWORD dst_unused:UNUSED_PAD src0_sel:WORD_1 src1_sel:DWORD
	v_and_b32_sdwa v21, v38, v177 dst_sel:DWORD dst_unused:UNUSED_PAD src0_sel:WORD_1 src1_sel:DWORD
	v_add3_u32 v23, v37, v23, s28
	v_add3_u32 v36, v36, v48, s28
	v_add3_u32 v21, v38, v21, s28
	v_add3_u32 v7, v39, v7, s28
	v_and_b32_e32 v23, 0xffff0000, v23
	v_and_b32_e32 v36, 0xffff0000, v36
	v_or_b32_sdwa v37, v23, v7 dst_sel:DWORD dst_unused:UNUSED_PAD src0_sel:DWORD src1_sel:WORD_1
	v_or_b32_sdwa v36, v36, v21 dst_sel:DWORD dst_unused:UNUSED_PAD src0_sel:DWORD src1_sel:WORD_1
	global_store_dwordx2 v[24:25], v[36:37], off
	v_lshl_add_u64 v[48:49], v[26:27], 0, v[18:19]
	s_waitcnt vmcnt(1)
	v_mov_b32_e32 v52, v86
	v_mov_b32_e32 v53, v87
	v_mov_b32_e32 v54, v88
	v_mov_b32_e32 v55, v89
	v_mov_b32_e32 v48, v82
	v_mov_b32_e32 v49, v83
	v_mov_b32_e32 v50, v84
	v_mov_b32_e32 v51, v85
	v_mov_b32_e32 v36, v78
	v_mov_b32_e32 v37, v79
	v_mov_b32_e32 v38, v80
	v_mov_b32_e32 v39, v81
	v_mov_b32_e32 v58, v40
	v_mov_b32_e32 v59, v42
	v_mov_b32_e32 v42, v41
	v_pk_mul_f32 v[40:41], v[58:59], v[56:57] op_sel_hi:[1,0]
	v_pk_mul_f32 v[42:43], v[42:43], v[56:57] op_sel_hi:[1,0]
	v_mov_b32_e32 v21, v1
	v_mov_b32_e32 v58, v36
	v_mov_b32_e32 v59, v38
	v_mov_b32_e32 v60, v48
	v_mov_b32_e32 v61, v50
	v_mov_b32_e32 v38, v37
	v_mov_b32_e32 v50, v49
	v_mov_b32_e32 v62, v52
	v_mov_b32_e32 v63, v54
	v_mov_b32_e32 v54, v53
	v_pk_mul_f32 v[36:37], v[40:41], v[58:59]
	v_pk_add_f32 v[40:41], v[60:61], 1.0 op_sel_hi:[1,0]
	v_pk_mul_f32 v[38:39], v[42:43], v[38:39]
	v_pk_add_f32 v[42:43], v[50:51], 1.0 op_sel_hi:[1,0]
	v_pk_fma_f32 v[36:37], v[36:37], v[40:41], v[62:63]
	v_pk_fma_f32 v[38:39], v[38:39], v[42:43], v[54:55]
	v_and_b32_sdwa v19, v36, v177 dst_sel:DWORD dst_unused:UNUSED_PAD src0_sel:WORD_1 src1_sel:DWORD
	v_and_b32_sdwa v23, v39, v177 dst_sel:DWORD dst_unused:UNUSED_PAD src0_sel:WORD_1 src1_sel:DWORD
	v_and_b32_sdwa v40, v38, v177 dst_sel:DWORD dst_unused:UNUSED_PAD src0_sel:WORD_1 src1_sel:DWORD
	v_and_b32_sdwa v7, v37, v177 dst_sel:DWORD dst_unused:UNUSED_PAD src0_sel:WORD_1 src1_sel:DWORD
	v_add3_u32 v19, v36, v19, s28
	v_add3_u32 v23, v39, v23, s28
	v_add3_u32 v36, v38, v40, s28
	v_add3_u32 v7, v37, v7, s28
	v_and_b32_e32 v23, 0xffff0000, v23
	v_and_b32_e32 v36, 0xffff0000, v36
	v_or_b32_sdwa v37, v23, v7 dst_sel:DWORD dst_unused:UNUSED_PAD src0_sel:DWORD src1_sel:WORD_1
	v_or_b32_sdwa v36, v36, v19 dst_sel:DWORD dst_unused:UNUSED_PAD src0_sel:DWORD src1_sel:WORD_1
	global_store_dwordx2 v[24:25], v[36:37], off offset:512
	v_lshl_add_u64 v[40:41], v[26:27], 0, v[20:21]
	v_mov_b32_e32 v48, v98
	v_mov_b32_e32 v49, v99
	v_mov_b32_e32 v50, v100
	v_mov_b32_e32 v51, v101
	v_mov_b32_e32 v40, v94
	v_mov_b32_e32 v41, v95
	v_mov_b32_e32 v42, v96
	v_mov_b32_e32 v43, v97
	v_mov_b32_e32 v36, v90
	v_mov_b32_e32 v37, v91
	v_mov_b32_e32 v38, v92
	v_mov_b32_e32 v39, v93
	v_mov_b32_e32 v52, v44
	v_mov_b32_e32 v53, v46
	v_mov_b32_e32 v44, v45
	v_mov_b32_e32 v45, v47
	v_pk_mul_f32 v[46:47], v[52:53], v[56:57] op_sel_hi:[1,0]
	v_pk_mul_f32 v[44:45], v[44:45], v[56:57] op_sel_hi:[1,0]
	v_mov_b32_e32 v23, v1
	v_lshl_add_u64 v[26:27], v[26:27], 0, v[22:23]
	v_mov_b32_e32 v52, v36
	v_mov_b32_e32 v53, v38
	v_mov_b32_e32 v54, v40
	v_mov_b32_e32 v55, v42
	v_mov_b32_e32 v38, v37
	v_mov_b32_e32 v42, v41
	v_mov_b32_e32 v58, v48
	v_mov_b32_e32 v59, v50
	v_mov_b32_e32 v50, v49
	v_pk_mul_f32 v[36:37], v[46:47], v[52:53]
	v_pk_add_f32 v[40:41], v[54:55], 1.0 op_sel_hi:[1,0]
	v_pk_mul_f32 v[38:39], v[44:45], v[38:39]
	v_pk_add_f32 v[42:43], v[42:43], 1.0 op_sel_hi:[1,0]
	v_pk_fma_f32 v[36:37], v[36:37], v[40:41], v[58:59]
	v_pk_fma_f32 v[38:39], v[38:39], v[42:43], v[50:51]
	v_and_b32_sdwa v19, v36, v177 dst_sel:DWORD dst_unused:UNUSED_PAD src0_sel:WORD_1 src1_sel:DWORD
	v_and_b32_sdwa v21, v39, v177 dst_sel:DWORD dst_unused:UNUSED_PAD src0_sel:WORD_1 src1_sel:DWORD
	v_and_b32_sdwa v40, v38, v177 dst_sel:DWORD dst_unused:UNUSED_PAD src0_sel:WORD_1 src1_sel:DWORD
	v_and_b32_sdwa v7, v37, v177 dst_sel:DWORD dst_unused:UNUSED_PAD src0_sel:WORD_1 src1_sel:DWORD
	v_add3_u32 v19, v36, v19, s28
	v_add3_u32 v21, v39, v21, s28
	v_add3_u32 v36, v38, v40, s28
	v_add3_u32 v7, v37, v7, s28
	v_and_b32_e32 v21, 0xffff0000, v21
	v_and_b32_e32 v36, 0xffff0000, v36
	v_or_b32_sdwa v37, v21, v7 dst_sel:DWORD dst_unused:UNUSED_PAD src0_sel:DWORD src1_sel:WORD_1
	v_or_b32_sdwa v36, v36, v19 dst_sel:DWORD dst_unused:UNUSED_PAD src0_sel:DWORD src1_sel:WORD_1
	global_store_dwordx2 v[24:25], v[36:37], off offset:1024
	v_mov_b32_e32 v26, v110
	v_mov_b32_e32 v27, v111
	v_mov_b32_e32 v28, v112
	v_mov_b32_e32 v29, v113
	v_mov_b32_e32 v40, v106
	v_mov_b32_e32 v41, v107
	v_mov_b32_e32 v42, v108
	v_mov_b32_e32 v43, v109
	v_mov_b32_e32 v36, v102
	v_mov_b32_e32 v37, v103
	v_mov_b32_e32 v38, v104
	v_mov_b32_e32 v39, v105
	v_mov_b32_e32 v44, v2
	v_mov_b32_e32 v45, v4
	v_mov_b32_e32 v4, v3
	v_pk_mul_f32 v[2:3], v[44:45], v[56:57] op_sel_hi:[1,0]
	v_pk_mul_f32 v[4:5], v[4:5], v[56:57] op_sel_hi:[1,0]
	v_mov_b32_e32 v47, v42
	v_mov_b32_e32 v45, v38
	v_mov_b32_e32 v38, v37
	v_mov_b32_e32 v42, v41
	v_mov_b32_e32 v44, v36
	v_mov_b32_e32 v46, v40
	v_mov_b32_e32 v49, v28
	v_mov_b32_e32 v28, v27
	v_pk_mul_f32 v[4:5], v[4:5], v[38:39]
	v_pk_add_f32 v[36:37], v[42:43], 1.0 op_sel_hi:[1,0]
	v_mov_b32_e32 v48, v26
	v_pk_mul_f32 v[2:3], v[2:3], v[44:45]
	v_pk_add_f32 v[26:27], v[46:47], 1.0 op_sel_hi:[1,0]
	v_pk_fma_f32 v[4:5], v[4:5], v[36:37], v[28:29]
	v_pk_fma_f32 v[2:3], v[2:3], v[26:27], v[48:49]
	v_and_b32_sdwa v21, v5, v177 dst_sel:DWORD dst_unused:UNUSED_PAD src0_sel:WORD_1 src1_sel:DWORD
	v_and_b32_sdwa v23, v4, v177 dst_sel:DWORD dst_unused:UNUSED_PAD src0_sel:WORD_1 src1_sel:DWORD
	v_and_b32_sdwa v7, v3, v177 dst_sel:DWORD dst_unused:UNUSED_PAD src0_sel:WORD_1 src1_sel:DWORD
	v_and_b32_sdwa v19, v2, v177 dst_sel:DWORD dst_unused:UNUSED_PAD src0_sel:WORD_1 src1_sel:DWORD
	v_add3_u32 v5, v5, v21, s28
	v_add3_u32 v4, v4, v23, s28
	v_add3_u32 v2, v2, v19, s28
	v_add3_u32 v3, v3, v7, s28
	v_and_b32_e32 v5, 0xffff0000, v5
	v_and_b32_e32 v4, 0xffff0000, v4
	v_or_b32_sdwa v3, v5, v3 dst_sel:DWORD dst_unused:UNUSED_PAD src0_sel:DWORD src1_sel:WORD_1
	v_or_b32_sdwa v2, v4, v2 dst_sel:DWORD dst_unused:UNUSED_PAD src0_sel:DWORD src1_sel:WORD_1
	global_store_dwordx2 v[24:25], v[2:3], off offset:1536
	s_nop 0
	v_lshl_add_u32 v6, s4, 3, v6
	v_cmp_lt_i32_e32 vcc, s29, v6
	s_or_b64 s[18:19], vcc, s[18:19]
	s_andn2_b64 exec, exec, s[18:19]
	s_cbranch_execz .LBB0_609

.LBB0_1379:
	s_or_b64 exec, exec, s[46:47]
	v_lshl_add_u64 v[2:3], v[2:3], 0, v[0:1]
	global_load_dwordx4 v[36:39], v[2:3], off
	global_load_dwordx4 v[40:43], v[2:3], off offset:1024
	global_load_dwordx4 v[44:47], v[2:3], off offset:2048
	s_nop 0
	global_load_dwordx4 v[2:5], v[2:3], off offset:3072
	s_nop 0
	global_load_dwordx4 v[48:51], v[8:9], off
	global_load_dwordx4 v[78:81], v[10:11], off
	global_load_dwordx4 v[90:93], v[12:13], off
	global_load_dwordx4 v[102:105], v[14:15], off
	v_min_i32_e32 v19, 0x4000, v6
	v_ashrrev_i32_e32 v19, 11, v19
	v_mul_hi_i32_i24_e32 v25, 0x9000, v19
	v_mul_i32_i24_e32 v24, 0x9000, v19
	v_lshl_add_u64 v[24:25], s[16:17], 0, v[24:25]
	v_lshl_add_u64 v[26:27], v[24:25], 0, s[38:39]
	v_lshl_add_u64 v[28:29], v[26:27], 0, v[0:1]
	global_load_dwordx4 v[52:55], v[28:29], off
	global_load_dwordx4 v[82:85], v[28:29], off offset:1024
	global_load_dwordx4 v[94:97], v[28:29], off offset:2048
	global_load_dwordx4 v[106:109], v[28:29], off offset:3072
	v_lshl_add_u64 v[28:29], v[24:25], 0, v[0:1]
	global_load_dwordx4 v[56:59], v[28:29], off
	global_load_dwordx4 v[86:89], v[28:29], off offset:1024
	global_load_dwordx4 v[98:101], v[28:29], off offset:2048
	global_load_dwordx4 v[110:113], v[28:29], off offset:3072
	s_mov_b32 s2, s42
	s_waitcnt vmcnt(15)
	v_mov_b32_e32 v60, v37
	s_waitcnt vmcnt(14)
	v_mov_b32_e32 v61, v41
	v_mov_b32_e32 v24, v36
	v_mov_b32_e32 v25, v40
	s_waitcnt vmcnt(13)
	v_mov_b32_e32 v68, v45
	s_waitcnt vmcnt(12)
	v_mov_b32_e32 v69, v3
	v_pk_mul_f32 v[60:61], v[60:61], v[60:61]
	v_mov_b32_e32 v62, v38
	v_mov_b32_e32 v63, v42
	v_mov_b32_e32 v66, v44
	v_mov_b32_e32 v67, v2
	v_pk_mul_f32 v[68:69], v[68:69], v[68:69]
	v_pk_fma_f32 v[24:25], v[24:25], v[24:25], v[60:61]
	v_mov_b32_e32 v64, v39
	v_mov_b32_e32 v65, v43
	v_mov_b32_e32 v70, v46
	v_mov_b32_e32 v71, v4
	v_pk_fma_f32 v[60:61], v[66:67], v[66:67], v[68:69]
	v_pk_fma_f32 v[24:25], v[62:63], v[62:63], v[24:25]
	v_mov_b32_e32 v72, v47
	v_mov_b32_e32 v73, v5
	v_pk_fma_f32 v[60:61], v[70:71], v[70:71], v[60:61]
	v_pk_fma_f32 v[24:25], v[64:65], v[64:65], v[24:25]
	v_pk_fma_f32 v[60:61], v[72:73], v[72:73], v[60:61]
	v_add_f32_e32 v19, v24, v25
	v_add_f32_e32 v19, v19, v60
	v_add_f32_e32 v19, v19, v61
	ds_bpermute_b32 v21, v30, v19
	v_lshlrev_b64 v[24:25], 11, v[6:7]
	s_waitcnt vmcnt(11)
	v_mov_b32_e32 v60, v48
	v_mov_b32_e32 v48, v36
	v_mov_b32_e32 v36, v37
	s_waitcnt lgkmcnt(0)
	v_add_f32_e32 v19, v19, v21
	ds_bpermute_b32 v21, v31, v19
	v_mov_b32_e32 v37, v39
	s_waitcnt vmcnt(3)
	v_mov_b32_e32 v62, v56
	v_mov_b32_e32 v61, v50
	v_mov_b32_e32 v50, v49
	s_waitcnt lgkmcnt(0)
	v_add_f32_e32 v21, v19, v21
	ds_bpermute_b32 v23, v32, v21
	v_mov_b32_e32 v49, v38
	v_mov_b32_e32 v39, v54
	v_mov_b32_e32 v54, v53
	v_mov_b32_e32 v38, v52
	s_waitcnt lgkmcnt(0)
	v_add_f32_e32 v7, v21, v23
	ds_bpermute_b32 v21, v33, v7
	v_mov_b32_e32 v63, v58
	v_mov_b32_e32 v58, v57
	v_pk_add_f32 v[52:53], v[54:55], 1.0 op_sel_hi:[1,0]
	v_pk_add_f32 v[38:39], v[38:39], 1.0 op_sel_hi:[1,0]
	s_waitcnt lgkmcnt(0)
	v_add_f32_e32 v7, v7, v21
	ds_bpermute_b32 v21, v34, v7
	v_lshl_add_u64 v[24:25], v[16:17], 0, v[24:25]
	v_mov_b32_e32 v19, v1
	s_waitcnt lgkmcnt(0)
	v_add_f32_e32 v7, v7, v21
	ds_bpermute_b32 v21, v35, v7
	s_waitcnt lgkmcnt(0)
	v_add_f32_e32 v7, v7, v21
	v_fmamk_f32 v7, v7, 0x3a800000, v174
	v_mul_f32_e32 v21, 0x4b800000, v7
	v_cmp_gt_f32_e32 vcc, s27, v7
	s_nop 1
	v_cndmask_b32_e32 v7, v7, v21, vcc
	v_rsq_f32_e32 v7, v7
	s_nop 0
	v_mul_f32_e32 v21, 0x45800000, v7
	v_cndmask_b32_e32 v56, v7, v21, vcc
	v_pk_mul_f32 v[36:37], v[36:37], v[56:57] op_sel_hi:[1,0]
	v_pk_mul_f32 v[48:49], v[48:49], v[56:57] op_sel_hi:[1,0]
	v_pk_mul_f32 v[36:37], v[50:51], v[36:37]
	v_pk_mul_f32 v[48:49], v[60:61], v[48:49]
	v_pk_fma_f32 v[36:37], v[52:53], v[36:37], v[58:59]
	v_pk_fma_f32 v[38:39], v[38:39], v[48:49], v[62:63]
	v_and_b32_sdwa v23, v37, v177 dst_sel:DWORD dst_unused:UNUSED_PAD src0_sel:WORD_1 src1_sel:DWORD
	v_and_b32_sdwa v48, v36, v177 dst_sel:DWORD dst_unused:UNUSED_PAD src0_sel:WORD_1 src1_sel:DWORD
	v_and_b32_sdwa v7, v39, v177 dst_sel:DWORD dst_unused:UNUSED_PAD src0_sel:WORD_1 src1_sel:DWORD
	v_and_b32_sdwa v21, v38, v177 dst_sel:DWORD dst_unused:UNUSED_PAD src0_sel:WORD_1 src1_sel:DWORD
	v_add3_u32 v23, v37, v23, s28
	v_add3_u32 v36, v36, v48, s28
	v_add3_u32 v21, v38, v21, s28
	v_add3_u32 v7, v39, v7, s28
	v_and_b32_e32 v23, 0xffff0000, v23
	v_and_b32_e32 v36, 0xffff0000, v36
	v_or_b32_sdwa v37, v23, v7 dst_sel:DWORD dst_unused:UNUSED_PAD src0_sel:DWORD src1_sel:WORD_1
	v_or_b32_sdwa v36, v36, v21 dst_sel:DWORD dst_unused:UNUSED_PAD src0_sel:DWORD src1_sel:WORD_1
	global_store_dwordx2 v[24:25], v[36:37], off
	v_lshl_add_u64 v[48:49], v[26:27], 0, v[18:19]
	s_waitcnt vmcnt(1)
	v_mov_b32_e32 v52, v86
	v_mov_b32_e32 v53, v87
	v_mov_b32_e32 v54, v88
	v_mov_b32_e32 v55, v89
	v_mov_b32_e32 v48, v82
	v_mov_b32_e32 v49, v83
	v_mov_b32_e32 v50, v84
	v_mov_b32_e32 v51, v85
	v_mov_b32_e32 v36, v78
	v_mov_b32_e32 v37, v79
	v_mov_b32_e32 v38, v80
	v_mov_b32_e32 v39, v81
	v_mov_b32_e32 v58, v40
	v_mov_b32_e32 v59, v42
	v_mov_b32_e32 v42, v41
	v_pk_mul_f32 v[40:41], v[58:59], v[56:57] op_sel_hi:[1,0]
	v_pk_mul_f32 v[42:43], v[42:43], v[56:57] op_sel_hi:[1,0]
	v_mov_b32_e32 v21, v1
	v_mov_b32_e32 v58, v36
	v_mov_b32_e32 v59, v38
	v_mov_b32_e32 v60, v48
	v_mov_b32_e32 v61, v50
	v_mov_b32_e32 v38, v37
	v_mov_b32_e32 v50, v49
	v_mov_b32_e32 v62, v52
	v_mov_b32_e32 v63, v54
	v_mov_b32_e32 v54, v53
	v_pk_mul_f32 v[36:37], v[40:41], v[58:59]
	v_pk_add_f32 v[40:41], v[60:61], 1.0 op_sel_hi:[1,0]
	v_pk_mul_f32 v[38:39], v[42:43], v[38:39]
	v_pk_add_f32 v[42:43], v[50:51], 1.0 op_sel_hi:[1,0]
	v_pk_fma_f32 v[36:37], v[36:37], v[40:41], v[62:63]
	v_pk_fma_f32 v[38:39], v[38:39], v[42:43], v[54:55]
	v_and_b32_sdwa v19, v36, v177 dst_sel:DWORD dst_unused:UNUSED_PAD src0_sel:WORD_1 src1_sel:DWORD
	v_and_b32_sdwa v23, v39, v177 dst_sel:DWORD dst_unused:UNUSED_PAD src0_sel:WORD_1 src1_sel:DWORD
	v_and_b32_sdwa v40, v38, v177 dst_sel:DWORD dst_unused:UNUSED_PAD src0_sel:WORD_1 src1_sel:DWORD
	v_and_b32_sdwa v7, v37, v177 dst_sel:DWORD dst_unused:UNUSED_PAD src0_sel:WORD_1 src1_sel:DWORD
	v_add3_u32 v19, v36, v19, s28
	v_add3_u32 v23, v39, v23, s28
	v_add3_u32 v36, v38, v40, s28
	v_add3_u32 v7, v37, v7, s28
	v_and_b32_e32 v23, 0xffff0000, v23
	v_and_b32_e32 v36, 0xffff0000, v36
	v_or_b32_sdwa v37, v23, v7 dst_sel:DWORD dst_unused:UNUSED_PAD src0_sel:DWORD src1_sel:WORD_1
	v_or_b32_sdwa v36, v36, v19 dst_sel:DWORD dst_unused:UNUSED_PAD src0_sel:DWORD src1_sel:WORD_1
	global_store_dwordx2 v[24:25], v[36:37], off offset:512
	v_lshl_add_u64 v[40:41], v[26:27], 0, v[20:21]
	v_mov_b32_e32 v48, v98
	v_mov_b32_e32 v49, v99
	v_mov_b32_e32 v50, v100
	v_mov_b32_e32 v51, v101
	v_mov_b32_e32 v40, v94
	v_mov_b32_e32 v41, v95
	v_mov_b32_e32 v42, v96
	v_mov_b32_e32 v43, v97
	v_mov_b32_e32 v36, v90
	v_mov_b32_e32 v37, v91
	v_mov_b32_e32 v38, v92
	v_mov_b32_e32 v39, v93
	v_mov_b32_e32 v52, v44
	v_mov_b32_e32 v53, v46
	v_mov_b32_e32 v44, v45
	v_mov_b32_e32 v45, v47
	v_pk_mul_f32 v[46:47], v[52:53], v[56:57] op_sel_hi:[1,0]
	v_pk_mul_f32 v[44:45], v[44:45], v[56:57] op_sel_hi:[1,0]
	v_mov_b32_e32 v23, v1
	v_lshl_add_u64 v[26:27], v[26:27], 0, v[22:23]
	v_mov_b32_e32 v52, v36
	v_mov_b32_e32 v53, v38
	v_mov_b32_e32 v54, v40
	v_mov_b32_e32 v55, v42
	v_mov_b32_e32 v38, v37
	v_mov_b32_e32 v42, v41
	v_mov_b32_e32 v58, v48
	v_mov_b32_e32 v59, v50
	v_mov_b32_e32 v50, v49
	v_pk_mul_f32 v[36:37], v[46:47], v[52:53]
	v_pk_add_f32 v[40:41], v[54:55], 1.0 op_sel_hi:[1,0]
	v_pk_mul_f32 v[38:39], v[44:45], v[38:39]
	v_pk_add_f32 v[42:43], v[42:43], 1.0 op_sel_hi:[1,0]
	v_pk_fma_f32 v[36:37], v[36:37], v[40:41], v[58:59]
	v_pk_fma_f32 v[38:39], v[38:39], v[42:43], v[50:51]
	v_and_b32_sdwa v19, v36, v177 dst_sel:DWORD dst_unused:UNUSED_PAD src0_sel:WORD_1 src1_sel:DWORD
	v_and_b32_sdwa v21, v39, v177 dst_sel:DWORD dst_unused:UNUSED_PAD src0_sel:WORD_1 src1_sel:DWORD
	v_and_b32_sdwa v40, v38, v177 dst_sel:DWORD dst_unused:UNUSED_PAD src0_sel:WORD_1 src1_sel:DWORD
	v_and_b32_sdwa v7, v37, v177 dst_sel:DWORD dst_unused:UNUSED_PAD src0_sel:WORD_1 src1_sel:DWORD
	v_add3_u32 v19, v36, v19, s28
	v_add3_u32 v21, v39, v21, s28
	v_add3_u32 v36, v38, v40, s28
	v_add3_u32 v7, v37, v7, s28
	v_and_b32_e32 v21, 0xffff0000, v21
	v_and_b32_e32 v36, 0xffff0000, v36
	v_or_b32_sdwa v37, v21, v7 dst_sel:DWORD dst_unused:UNUSED_PAD src0_sel:DWORD src1_sel:WORD_1
	v_or_b32_sdwa v36, v36, v19 dst_sel:DWORD dst_unused:UNUSED_PAD src0_sel:DWORD src1_sel:WORD_1
	global_store_dwordx2 v[24:25], v[36:37], off offset:1024
	v_mov_b32_e32 v26, v110
	v_mov_b32_e32 v27, v111
	v_mov_b32_e32 v28, v112
	v_mov_b32_e32 v29, v113
	v_mov_b32_e32 v40, v106
	v_mov_b32_e32 v41, v107
	v_mov_b32_e32 v42, v108
	v_mov_b32_e32 v43, v109
	v_mov_b32_e32 v36, v102
	v_mov_b32_e32 v37, v103
	v_mov_b32_e32 v38, v104
	v_mov_b32_e32 v39, v105
	v_mov_b32_e32 v44, v2
	v_mov_b32_e32 v45, v4
	v_mov_b32_e32 v4, v3
	v_pk_mul_f32 v[2:3], v[44:45], v[56:57] op_sel_hi:[1,0]
	v_pk_mul_f32 v[4:5], v[4:5], v[56:57] op_sel_hi:[1,0]
	v_mov_b32_e32 v47, v42
	v_mov_b32_e32 v45, v38
	v_mov_b32_e32 v38, v37
	v_mov_b32_e32 v42, v41
	v_mov_b32_e32 v44, v36
	v_mov_b32_e32 v46, v40
	v_mov_b32_e32 v49, v28
	v_mov_b32_e32 v28, v27
	v_pk_mul_f32 v[4:5], v[4:5], v[38:39]
	v_pk_add_f32 v[36:37], v[42:43], 1.0 op_sel_hi:[1,0]
	v_mov_b32_e32 v48, v26
	v_pk_mul_f32 v[2:3], v[2:3], v[44:45]
	v_pk_add_f32 v[26:27], v[46:47], 1.0 op_sel_hi:[1,0]
	v_pk_fma_f32 v[4:5], v[4:5], v[36:37], v[28:29]
	v_pk_fma_f32 v[2:3], v[2:3], v[26:27], v[48:49]
	v_and_b32_sdwa v21, v5, v177 dst_sel:DWORD dst_unused:UNUSED_PAD src0_sel:WORD_1 src1_sel:DWORD
	v_and_b32_sdwa v23, v4, v177 dst_sel:DWORD dst_unused:UNUSED_PAD src0_sel:WORD_1 src1_sel:DWORD
	v_and_b32_sdwa v7, v3, v177 dst_sel:DWORD dst_unused:UNUSED_PAD src0_sel:WORD_1 src1_sel:DWORD
	v_and_b32_sdwa v19, v2, v177 dst_sel:DWORD dst_unused:UNUSED_PAD src0_sel:WORD_1 src1_sel:DWORD
	v_add3_u32 v5, v5, v21, s28
	v_add3_u32 v4, v4, v23, s28
	v_add3_u32 v2, v2, v19, s28
	v_add3_u32 v3, v3, v7, s28
	v_and_b32_e32 v5, 0xffff0000, v5
	v_and_b32_e32 v4, 0xffff0000, v4
	v_or_b32_sdwa v3, v5, v3 dst_sel:DWORD dst_unused:UNUSED_PAD src0_sel:DWORD src1_sel:WORD_1
	v_or_b32_sdwa v2, v4, v2 dst_sel:DWORD dst_unused:UNUSED_PAD src0_sel:DWORD src1_sel:WORD_1
	global_store_dwordx2 v[24:25], v[2:3], off offset:1536
	s_nop 0
	v_lshl_add_u32 v6, s2, 3, v6
	v_cmp_le_i32_e32 vcc, s11, v6
	s_or_b64 s[18:19], vcc, s[18:19]
	s_andn2_b64 exec, exec, s[18:19]
	s_cbranch_execz .LBB0_1384
